# phase 3b: layer-1 modulation GEMV shared by all 256 workgroups (one 48-column item each), weight conversion stays on workgroups 128-255
# speedup vs baseline: 1.0092x; 1.0092x over previous
; __device__ __forceinline__ float siluf_(float x) { return x / (1.f + __expf(-x)); }
; #define SEAM(k) do { if (IN(k) && IN((k) + 1)) GSYNC(); } while (0)
; __device__ __forceinline__ void phase_mod(const Params& p, unsigned char* lds, const int layer, const int wb0, const int nwb) {
;     ...
;     __syncthreads();
;     for (int e = tid; e < 5 * D; e += 512) { const int r = e / D, k = e % D; const float v = r < 4 ? p.c[r * D + k] : p.c_ctx[k]; sc[e] = siluf_(v); }
;     __syncthreads();
;     for (int it = (int)blockIdx.x - wb0; it < 256; it += nwb) {
; __global__ void __launch_bounds__(512, 2) fwd_megakernel(Params p) {
;     ...
;         { const int wb0 = gridDim.x >= 256 ? 128 : 0, nwb = gridDim.x - wb0; if ((int)blockIdx.x >= wb0) { phase_convert(p, lds, 1, wb0, nwb); phase_mod(p, lds, 1, wb0, nwb); } } } } } SEAM(3);
.Lmod_all:
.LBB0_586:
	s_or_b64 exec, exec, s[0:1]
	v_readlane_b32 s52, v241, 1
	v_mov_b32_e32 v65, 0
	v_readlane_b32 s54, v241, 3
	v_readlane_b32 s55, v241, 4
	v_readlane_b32 s58, v241, 7
	v_readlane_b32 s59, v241, 8
	v_lshl_add_u64 v[0:1], s[54:55], 0, v[64:65]
	s_mov_b64 s[0:1], 0
	s_movk_i32 s4, 0x2000
	s_mov_b64 s[2:3], 0x800
	s_movk_i32 s5, 0x25ff
	v_mov_b32_e32 v2, v162
	s_barrier
	s_barrier
	s_mov_b32 s10, 0
	s_mov_b32 s18, s92
	s_mov_b32 s19, s82
	v_readlane_b32 s53, v241, 2
	v_readlane_b32 s56, v241, 5
	v_readlane_b32 s57, v241, 6
	v_readlane_b32 s60, v241, 9
	v_readlane_b32 s61, v241, 10
	v_readlane_b32 s62, v241, 11
	v_readlane_b32 s63, v241, 12
	v_readlane_b32 s64, v241, 13
	v_readlane_b32 s65, v241, 14
	v_readlane_b32 s66, v241, 15
	v_readlane_b32 s67, v241, 16

; __device__ __forceinline__ unsigned pk2(float lo, float hi) { return __builtin_bit_cast(unsigned, __builtin_convertvector((f32x2){lo, hi}, hwbf16x2)); }
; __device__ __forceinline__ void phase_na(const Params& p, unsigned char* lds) {
;     ...
;             __syncthreads();
;         }
;         { bf16_t* ost = KtB + w * (32 * 136);
; #pragma unroll
;           for (int mt = 0; mt < 2; ++mt) {
;             float l = lrow[mt]; l += __shfl_xor(l, 16); l += __shfl_xor(l, 32); const float inv = 1.f / l;
; #pragma unroll
;             for (int dt = 0; dt < 8; ++dt) *(u32x2*)(ost + (mt * 16 + fr) * 136 + dt * 16 + fq * 4) = (u32x2){pk2(Oa[mt][dt][0] * inv, Oa[mt][dt][1] * inv), pk2(Oa[mt][dt][2] * inv, Oa[mt][dt][3] * inv)}; }
;           asm volatile("s_waitcnt lgkmcnt(0)" ::: "memory");
;           const int q = lane >> 1, hf = lane & 1;
;           bf16_t* op = O + (size_t)(b * SEQ + qr * 64 + qc0 + q) * D + h * 128 + hf * 64;
; #pragma unroll
;           for (int e = 0; e < 8; ++e) *(u32x4*)(op + e * 8) = *(const u32x4*)(ost + q * 136 + hf * 64 + e * 8); }
.Lna_after:
.Lna_tile_end:
	s_waitcnt lgkmcnt(0)
	s_barrier
	s_mov_b32 s65, s66
	s_add_i32 s66, s66, 1
	s_cmp_eq_u32 s66, 3
	s_cselect_b32 s66, 0, s66
	s_add_i32 s21, s21, 1
	s_cmp_lt_u32 s21, s18
	s_cbranch_scc1 .Lna_tile
	ds_bpermute_b32 v232, v218, v224
	ds_bpermute_b32 v233, v218, v225
	s_waitcnt lgkmcnt(0)
	v_add_f32_e32 v232, v232, v224
	v_add_f32_e32 v233, v233, v225
	ds_bpermute_b32 v234, v219, v232
	ds_bpermute_b32 v235, v219, v233
	s_waitcnt lgkmcnt(0)
	v_add_f32_e32 v232, v232, v234
	v_add_f32_e32 v233, v233, v235
	v_rcp_f32_e32 v234, v232
	s_nop 0
	v_fma_f32 v236, -v232, v234, 1.0
	v_fma_f32 v234, v236, v234, v234
	v_rcp_f32_e32 v235, v233
	s_nop 0
	v_fma_f32 v237, -v233, v235, 1.0
	v_fma_f32 v235, v237, v235, v235
	s_mul_i32 s0, s10, 0x2200
	v_and_b32_e32 v238, 15, v162
	v_mul_u32_u24_e32 v238, 0x110, v238
	v_bfe_u32 v239, v162, 4, 2
	v_lshl_add_u32 v238, v239, 3, v238
	v_add_u32_e32 v238, s0, v238
	v_mul_f32_e32 v32, v32, v234
	v_mul_f32_e32 v33, v33, v234
	v_mul_f32_e32 v34, v34, v234
	v_mul_f32_e32 v35, v35, v234
	v_cvt_pk_bf16_f32 v32, v32, v33
	v_cvt_pk_bf16_f32 v33, v34, v35
	ds_write_b64 v238, v[32:33] offset:0
	v_mul_f32_e32 v36, v36, v234
	v_mul_f32_e32 v37, v37, v234
	v_mul_f32_e32 v38, v38, v234
	v_mul_f32_e32 v39, v39, v234
	v_cvt_pk_bf16_f32 v36, v36, v37
	v_cvt_pk_bf16_f32 v37, v38, v39
	ds_write_b64 v238, v[36:37] offset:32
	v_mul_f32_e32 v40, v40, v234
	v_mul_f32_e32 v41, v41, v234
	v_mul_f32_e32 v42, v42, v234
	v_mul_f32_e32 v43, v43, v234
	v_cvt_pk_bf16_f32 v40, v40, v41
	v_cvt_pk_bf16_f32 v41, v42, v43
	ds_write_b64 v238, v[40:41] offset:64
	v_mul_f32_e32 v44, v44, v234
	v_mul_f32_e32 v45, v45, v234
	v_mul_f32_e32 v46, v46, v234
	v_mul_f32_e32 v47, v47, v234
	v_cvt_pk_bf16_f32 v44, v44, v45
	v_cvt_pk_bf16_f32 v45, v46, v47
	ds_write_b64 v238, v[44:45] offset:96
	v_mul_f32_e32 v48, v48, v234
	v_mul_f32_e32 v49, v49, v234
	v_mul_f32_e32 v50, v50, v234
	v_mul_f32_e32 v51, v51, v234
	v_cvt_pk_bf16_f32 v48, v48, v49
	v_cvt_pk_bf16_f32 v49, v50, v51
	ds_write_b64 v238, v[48:49] offset:128
	v_mul_f32_e32 v52, v52, v234
	v_mul_f32_e32 v53, v53, v234
	v_mul_f32_e32 v54, v54, v234
	v_mul_f32_e32 v55, v55, v234
	v_cvt_pk_bf16_f32 v52, v52, v53
	v_cvt_pk_bf16_f32 v53, v54, v55
	ds_write_b64 v238, v[52:53] offset:160
	v_mul_f32_e32 v56, v56, v234
	v_mul_f32_e32 v57, v57, v234
	v_mul_f32_e32 v58, v58, v234
	v_mul_f32_e32 v59, v59, v234
	v_cvt_pk_bf16_f32 v56, v56, v57
	v_cvt_pk_bf16_f32 v57, v58, v59
	ds_write_b64 v238, v[56:57] offset:192
	v_mul_f32_e32 v60, v60, v234
	v_mul_f32_e32 v61, v61, v234
	v_mul_f32_e32 v62, v62, v234
	v_mul_f32_e32 v63, v63, v234
	v_cvt_pk_bf16_f32 v60, v60, v61
	v_cvt_pk_bf16_f32 v61, v62, v63
	ds_write_b64 v238, v[60:61] offset:224
	v_mul_f32_e32 v64, v64, v235
	v_mul_f32_e32 v65, v65, v235
	v_mul_f32_e32 v66, v66, v235
	v_mul_f32_e32 v67, v67, v235
	v_cvt_pk_bf16_f32 v64, v64, v65
	v_cvt_pk_bf16_f32 v65, v66, v67
	ds_write_b64 v238, v[64:65] offset:4352
	v_mul_f32_e32 v68, v68, v235
	v_mul_f32_e32 v69, v69, v235
	v_mul_f32_e32 v70, v70, v235
	v_mul_f32_e32 v71, v71, v235
	v_cvt_pk_bf16_f32 v68, v68, v69
	v_cvt_pk_bf16_f32 v69, v70, v71
	ds_write_b64 v238, v[68:69] offset:4384
	v_mul_f32_e32 v72, v72, v235
	v_mul_f32_e32 v73, v73, v235
	v_mul_f32_e32 v74, v74, v235
	v_mul_f32_e32 v75, v75, v235
	v_cvt_pk_bf16_f32 v72, v72, v73
	v_cvt_pk_bf16_f32 v73, v74, v75
	ds_write_b64 v238, v[72:73] offset:4416
	v_mul_f32_e32 v76, v76, v235
	v_mul_f32_e32 v77, v77, v235
	v_mul_f32_e32 v78, v78, v235
	v_mul_f32_e32 v79, v79, v235
	v_cvt_pk_bf16_f32 v76, v76, v77
	v_cvt_pk_bf16_f32 v77, v78, v79
	ds_write_b64 v238, v[76:77] offset:4448
	v_mul_f32_e32 v80, v80, v235
	v_mul_f32_e32 v81, v81, v235
	v_mul_f32_e32 v82, v82, v235
	v_mul_f32_e32 v83, v83, v235
	v_cvt_pk_bf16_f32 v80, v80, v81
	v_cvt_pk_bf16_f32 v81, v82, v83
	ds_write_b64 v238, v[80:81] offset:4480
	v_mul_f32_e32 v84, v84, v235
	v_mul_f32_e32 v85, v85, v235
	v_mul_f32_e32 v86, v86, v235
	v_mul_f32_e32 v87, v87, v235
	v_cvt_pk_bf16_f32 v84, v84, v85
	v_cvt_pk_bf16_f32 v85, v86, v87
	ds_write_b64 v238, v[84:85] offset:4512
	v_mul_f32_e32 v88, v88, v235
	v_mul_f32_e32 v89, v89, v235
	v_mul_f32_e32 v90, v90, v235
	v_mul_f32_e32 v91, v91, v235
	v_cvt_pk_bf16_f32 v88, v88, v89
	v_cvt_pk_bf16_f32 v89, v90, v91
	ds_write_b64 v238, v[88:89] offset:4544
	v_mul_f32_e32 v92, v92, v235
	v_mul_f32_e32 v93, v93, v235
	v_mul_f32_e32 v94, v94, v235
	v_mul_f32_e32 v95, v95, v235
	v_cvt_pk_bf16_f32 v92, v92, v93
	v_cvt_pk_bf16_f32 v93, v94, v95
	ds_write_b64 v238, v[92:93] offset:4576
	s_waitcnt lgkmcnt(0)
	v_and_b32_e32 v232, 63, v162
	v_lshrrev_b32_e32 v233, 1, v232
	v_and_b32_e32 v234, 1, v232
	v_mul_u32_u24_e32 v235, 0x110, v233
	v_lshl_add_u32 v235, v234, 7, v235
	v_add_u32_e32 v235, s0, v235
	ds_read_b128 v[128:131], v235 offset:0
	ds_read_b128 v[132:135], v235 offset:16
	ds_read_b128 v[136:139], v235 offset:32
	ds_read_b128 v[140:143], v235 offset:48
	ds_read_b128 v[144:147], v235 offset:64
	ds_read_b128 v[148:151], v235 offset:80
	ds_read_b128 v[152:155], v235 offset:96
	ds_read_b128 v[156:159], v235 offset:112
	s_lshl_b32 s0, s15, 12
	s_lshl_b32 s1, s19, 6
	s_add_i32 s0, s0, s1
	s_add_i32 s0, s0, s12
	v_add_u32_e32 v233, s0, v233
	v_lshlrev_b32_e32 v233, 12, v233
	v_lshl_add_u32 v233, v234, 7, v233
	s_lshl_b32 s1, s14, 8
	v_add_u32_e32 v233, s1, v233
	s_waitcnt lgkmcnt(7)
	global_store_dwordx4 v233, v[128:131], s[8:9] offset:0
	s_waitcnt lgkmcnt(6)
	global_store_dwordx4 v233, v[132:135], s[8:9] offset:16
	s_waitcnt lgkmcnt(5)
	global_store_dwordx4 v233, v[136:139], s[8:9] offset:32
	s_waitcnt lgkmcnt(4)
	global_store_dwordx4 v233, v[140:143], s[8:9] offset:48
	s_waitcnt lgkmcnt(3)
	global_store_dwordx4 v233, v[144:147], s[8:9] offset:64
	s_waitcnt lgkmcnt(2)
	global_store_dwordx4 v233, v[148:151], s[8:9] offset:80
	s_waitcnt lgkmcnt(1)
	global_store_dwordx4 v233, v[152:155], s[8:9] offset:96
	s_waitcnt lgkmcnt(0)
	global_store_dwordx4 v233, v[156:159], s[8:9] offset:112
	s_add_i32 s13, s13, s82
	s_branch .Lna_unit
